# one s_nop pad after the MLA unit loop: flips the 8-byte code phase of the NA, GEMM and conversion code only
# baseline (speedup 1.0000x reference)
; __global__ void __launch_bounds__(NWAVES * 64, 2) fwd_mega(Args args) {
;     ...
;         } else if (EN_NA && kind == 2) {
;             for (int rep = 0; rep < REP_NA; ++rep) for (int u = vcu; u < 1024; u += G) {
.LBB0_271:
	s_nop 0
	s_mov_b64 s[6:7], 0
